# attention PV sections (DA + GQA inner loops): V-fragment ds_reads software-pipelined 3 ahead with rotating registers and counted lgkmcnt(3) instead of read-wait-MFMA lockstep
# baseline (speedup 1.0000x reference)
.LBB0_785:
	v_mov_b32_e32 v136, v111
	v_pk_mul_f32 v[146:147], v[136:137], s[94:95] op_sel_hi:[1,0]
	s_add_i32 s33, s33, 1
	v_fma_f32 v0, v96, s94, -v147
	v_exp_f32_e32 v136, v0
	v_fma_f32 v0, v80, s94, -v147
	v_exp_f32_e32 v145, v0
	v_fma_f32 v0, v97, s94, -v147
	v_exp_f32_e32 v148, v0
	v_fma_f32 v0, v81, s94, -v147
	v_exp_f32_e32 v0, v0
	v_add_f32_e32 v149, v136, v145
	v_fma_f32 v15, v98, s94, -v147
	s_xor_b32 s36, s36, 1
	v_pk_add_f32 v[80:81], v[148:149], v[0:1]
	v_exp_f32_e32 v149, v15
	v_fma_f32 v15, v82, s94, -v147
	v_exp_f32_e32 v152, v15
	v_fma_f32 v15, v99, s94, -v147
	v_pk_add_f32 v[80:81], v[80:81], v[80:81] op_sel_hi:[0,1]
	v_exp_f32_e32 v96, v15
	v_fma_f32 v15, v83, s94, -v147
	v_exp_f32_e32 v80, v15
	v_add_f32_e32 v97, v149, v152
	v_fma_f32 v15, v100, s94, -v147
	s_mulk_i32 s36, 0x6800
	v_pk_add_f32 v[82:83], v[96:97], v[80:81]
	v_exp_f32_e32 v81, v15
	v_fma_f32 v15, v84, s94, -v147
	v_exp_f32_e32 v97, v15
	v_fma_f32 v15, v101, s94, -v147
	v_pk_add_f32 v[82:83], v[82:83], v[82:83] op_sel_hi:[0,1]
	v_exp_f32_e32 v98, v15
	v_fma_f32 v15, v85, s94, -v147
	v_exp_f32_e32 v82, v15
	v_add_f32_e32 v99, v81, v97
	v_fma_f32 v15, v102, s94, -v147
	s_add_u32 s6, s6, s34
	v_pk_add_f32 v[84:85], v[98:99], v[82:83]
	v_exp_f32_e32 v83, v15
	v_fma_f32 v15, v86, s94, -v147
	v_exp_f32_e32 v99, v15
	v_fma_f32 v15, v103, s94, -v147
	v_pk_add_f32 v[100:101], v[84:85], v[84:85] op_sel_hi:[0,1]
	v_exp_f32_e32 v84, v15
	v_fma_f32 v15, v87, s94, -v147
	v_exp_f32_e32 v100, v15
	v_add_f32_e32 v85, v83, v99
	v_fma_f32 v15, v104, s94, -v147
	s_addc_u32 s7, s7, 0
	v_pk_add_f32 v[86:87], v[84:85], v[100:101]
	v_exp_f32_e32 v85, v15
	v_fma_f32 v15, v88, s94, -v147
	v_exp_f32_e32 v101, v15
	v_fma_f32 v15, v105, s94, -v147
	v_pk_add_f32 v[102:103], v[86:87], v[86:87] op_sel_hi:[0,1]
	v_exp_f32_e32 v86, v15
	v_fma_f32 v15, v89, s94, -v147
	v_exp_f32_e32 v102, v15
	v_add_f32_e32 v87, v85, v101
	v_fma_f32 v15, v106, s94, -v147
	s_cmp_eq_u32 s35, s33
	v_pk_add_f32 v[88:89], v[86:87], v[102:103]
	v_exp_f32_e32 v87, v15
	v_fma_f32 v15, v90, s94, -v147
	v_exp_f32_e32 v103, v15
	v_fma_f32 v15, v107, s94, -v147
	v_pk_add_f32 v[104:105], v[88:89], v[88:89] op_sel_hi:[0,1]
	v_exp_f32_e32 v150, v15
	v_fma_f32 v15, v91, s94, -v147
	v_exp_f32_e32 v104, v15
	v_add_f32_e32 v151, v87, v103
	v_fma_f32 v15, v108, s94, -v147
	v_pk_add_f32 v[88:89], v[150:151], v[104:105]
	v_exp_f32_e32 v105, v15
	v_fma_f32 v15, v92, s94, -v147
	v_exp_f32_e32 v151, v15
	v_fma_f32 v15, v109, s94, -v147
	v_pk_add_f32 v[106:107], v[88:89], v[88:89] op_sel_hi:[0,1]
	v_exp_f32_e32 v90, v15
	v_fma_f32 v15, v93, s94, -v147
	v_exp_f32_e32 v106, v15
	v_add_f32_e32 v91, v105, v151
	v_fma_f32 v15, v110, s94, -v147
	v_cvt_pk_bf16_f32 v93, v149, v96
	v_pk_add_f32 v[88:89], v[90:91], v[106:107]
	v_exp_f32_e32 v91, v15
	v_fma_f32 v15, v94, s94, -v147
	v_exp_f32_e32 v107, v15
	v_sub_f32_e32 v15, v146, v147
	v_pk_add_f32 v[108:109], v[88:89], v[88:89] op_sel_hi:[0,1]
	v_exp_f32_e32 v110, v15
	v_fma_f32 v15, v95, s94, -v147
	v_exp_f32_e32 v108, v15
	v_add_f32_e32 v111, v91, v107
	v_cvt_pk_bf16_f32 v95, v83, v84
	v_cvt_pk_bf16_f32 v84, v145, v0
	v_pk_add_f32 v[88:89], v[110:111], v[108:109]
	v_add3_u32 v0, s37, v213, v168
	v_add_f32_e32 v15, v88, v89
	v_fmac_f32_e32 v15, v144, v14
	v_add_u32_e32 v14, 0x2000, v0
	v_cvt_pk_bf16_f32 v94, v81, v98
	v_cvt_pk_bf16_f32 v88, v85, v86
	v_cvt_pk_bf16_f32 v89, v87, v150
	v_cvt_pk_bf16_f32 v85, v152, v80
	v_cvt_pk_bf16_f32 v86, v97, v82
	v_cvt_pk_bf16_f32 v87, v99, v100
	v_cvt_pk_bf16_f32 v80, v101, v102
	v_cvt_pk_bf16_f32 v81, v103, v104
	ds_read2_b64 v[96:99], v14 offset0:128 offset1:130
	ds_read2_b64 v[100:103], v14 offset0:132 offset1:134
	ds_read2_b64 v[144:147], v14 offset0:136 offset1:138
	ds_read2_b64 v[152:155], v14 offset0:140 offset1:142
	v_cvt_pk_bf16_f32 v92, v136, v148
	v_cvt_pk_bf16_f32 v90, v105, v90
	v_cvt_pk_bf16_f32 v91, v91, v110
	s_waitcnt lgkmcnt(4)
	s_waitcnt lgkmcnt(3)
	v_mfma_f32_32x32x16_bf16 v[64:79], v[96:99], v[92:95], v[64:79]
	v_add_u32_e32 v250, 0x3000, v0
	ds_read2_b64 v[156:159], v250 offset0:160 offset1:162
	v_cvt_pk_bf16_f32 v82, v151, v106
	v_cvt_pk_bf16_f32 v83, v107, v108
	s_waitcnt lgkmcnt(3)
	v_mfma_f32_32x32x16_bf16 v[64:79], v[100:103], v[88:91], v[64:79]
	v_add_u32_e32 v250, 0x3000, v0
	ds_read2_b64 v[160:163], v250 offset0:164 offset1:166
	s_waitcnt lgkmcnt(3)
	v_mfma_f32_32x32x16_bf16 v[64:79], v[144:147], v[84:87], v[64:79]
	v_add_u32_e32 v250, 0x3000, v0
	ds_read2_b64 v[144:147], v250 offset0:168 offset1:170
	v_add_u32_e32 v14, 0x3000, v0
	s_waitcnt lgkmcnt(3)
	v_mfma_f32_32x32x16_bf16 v[64:79], v[152:155], v[80:83], v[64:79]
	ds_read2_b64 v[152:155], v14 offset0:172 offset1:174
	s_waitcnt lgkmcnt(3)
	v_mfma_f32_32x32x16_bf16 v[48:63], v[156:159], v[92:95], v[48:63]
	v_add_u32_e32 v250, 0x4000, v0
	ds_read2_b64 v[156:159], v250 offset0:192 offset1:194
	s_waitcnt lgkmcnt(3)
	v_mfma_f32_32x32x16_bf16 v[48:63], v[160:163], v[88:91], v[48:63]
	v_add_u32_e32 v250, 0x4000, v0
	ds_read2_b64 v[160:163], v250 offset0:196 offset1:198
	s_waitcnt lgkmcnt(3)
	v_mfma_f32_32x32x16_bf16 v[48:63], v[144:147], v[84:87], v[48:63]
	v_add_u32_e32 v250, 0x4000, v0
	ds_read2_b64 v[144:147], v250 offset0:200 offset1:202
	v_add_u32_e32 v14, 0x4000, v0
	v_add_u32_e32 v0, 0x5000, v0
	s_waitcnt lgkmcnt(3)
	v_mfma_f32_32x32x16_bf16 v[48:63], v[152:155], v[80:83], v[48:63]
	ds_read2_b64 v[152:155], v14 offset0:204 offset1:206
	s_waitcnt lgkmcnt(3)
	v_mfma_f32_32x32x16_bf16 v[32:47], v[156:159], v[92:95], v[32:47]
	ds_read2_b64 v[156:159], v0 offset0:224 offset1:226
	s_waitcnt lgkmcnt(3)
	v_mfma_f32_32x32x16_bf16 v[32:47], v[160:163], v[88:91], v[32:47]
	ds_read2_b64 v[160:163], v0 offset0:228 offset1:230
	s_waitcnt lgkmcnt(3)
	v_mfma_f32_32x32x16_bf16 v[32:47], v[144:147], v[84:87], v[32:47]
	ds_read2_b64 v[144:147], v0 offset0:232 offset1:234
	s_waitcnt lgkmcnt(3)
	v_mfma_f32_32x32x16_bf16 v[32:47], v[152:155], v[80:83], v[32:47]
	s_waitcnt lgkmcnt(2)
	v_mfma_f32_32x32x16_bf16 v[16:31], v[156:159], v[92:95], v[16:31]
	s_waitcnt lgkmcnt(1)
	v_mfma_f32_32x32x16_bf16 v[16:31], v[160:163], v[88:91], v[16:31]
	s_waitcnt lgkmcnt(0)
	v_mfma_f32_32x32x16_bf16 v[16:31], v[144:147], v[84:87], v[16:31]
	ds_read2_b64 v[84:87], v0 offset0:236 offset1:238
	v_add_u32_e32 v0, s36, v214
	s_waitcnt vmcnt(2)
	ds_write_b128 v0, v[10:13]
	v_add_u32_e32 v0, s36, v143
	s_waitcnt vmcnt(1)
	ds_write_b16 v0, v6 offset:9216
	ds_write_b16_d16_hi v0, v6 offset:9352
	ds_write_b16 v0, v7 offset:9488
	ds_write_b16_d16_hi v0, v7 offset:9624
	ds_write_b16 v0, v8 offset:9760
	ds_write_b16_d16_hi v0, v8 offset:9896
	ds_write_b16 v0, v9 offset:10032
	ds_write_b16_d16_hi v0, v9 offset:10168
	s_waitcnt vmcnt(0)
	ds_write_b16 v0, v2 offset:10304
	ds_write_b16_d16_hi v0, v2 offset:10440
	ds_write_b16 v0, v3 offset:10576
	ds_write_b16_d16_hi v0, v3 offset:10712
	ds_write_b16 v0, v4 offset:10848
	ds_write_b16_d16_hi v0, v4 offset:10984
	ds_write_b16 v0, v5 offset:11120
	ds_write_b16_d16_hi v0, v5 offset:11256
	s_waitcnt lgkmcnt(0)
	s_barrier
	v_mfma_f32_32x32x16_bf16 v[16:31], v[84:87], v[80:83], v[16:31]
	s_cbranch_scc1 .LBB0_787
	v_mov_b32_e32 v144, v15
	s_branch .LBB0_783

.LBB0_810:
	v_mov_b32_e32 v146, v97
	v_pk_mul_f32 v[158:159], v[146:147], s[92:93] op_sel_hi:[1,0]
	s_xor_b32 s10, s10, 1
	v_fma_f32 v0, v82, s92, -v159
	v_exp_f32_e32 v157, v0
	v_fma_f32 v0, v66, s92, -v159
	v_exp_f32_e32 v175, v0
	v_fma_f32 v0, v83, s92, -v159
	v_exp_f32_e32 v160, v0
	v_fma_f32 v0, v67, s92, -v159
	v_exp_f32_e32 v0, v0
	v_add_f32_e32 v161, v157, v175
	s_mul_i32 s10, s10, 0x8800
	s_add_i32 s7, s7, 1
	v_pk_add_f32 v[66:67], v[160:161], v[0:1]
	s_nop 0
	v_pk_add_f32 v[66:67], v[66:67], v[66:67] op_sel_hi:[0,1]
	v_fma_f32 v66, v84, s92, -v159
	v_exp_f32_e32 v161, v66
	v_fma_f32 v66, v68, s92, -v159
	v_exp_f32_e32 v183, v66
	v_fma_f32 v66, v85, s92, -v159
	v_exp_f32_e32 v82, v66
	v_fma_f32 v66, v69, s92, -v159
	v_exp_f32_e32 v66, v66
	v_add_f32_e32 v83, v161, v183
	v_pk_add_f32 v[68:69], v[82:83], v[66:67]
	s_nop 0
	v_pk_add_f32 v[68:69], v[68:69], v[68:69] op_sel_hi:[0,1]
	v_fma_f32 v68, v70, s92, -v159
	v_fma_f32 v67, v86, s92, -v159
	v_exp_f32_e32 v83, v68
	v_fma_f32 v68, v87, s92, -v159
	v_exp_f32_e32 v67, v67
	v_exp_f32_e32 v84, v68
	v_fma_f32 v68, v71, s92, -v159
	v_exp_f32_e32 v68, v68
	v_add_f32_e32 v85, v67, v83
	v_pk_add_f32 v[70:71], v[84:85], v[68:69]
	s_nop 0
	v_pk_add_f32 v[86:87], v[70:71], v[70:71] op_sel_hi:[0,1]
	v_fma_f32 v69, v88, s92, -v159
	v_fma_f32 v70, v72, s92, -v159
	v_exp_f32_e32 v69, v69
	v_exp_f32_e32 v85, v70
	v_fma_f32 v70, v89, s92, -v159
	v_fma_f32 v72, v73, s92, -v159
	v_exp_f32_e32 v70, v70
	v_exp_f32_e32 v86, v72
	v_add_f32_e32 v71, v69, v85
	v_pk_add_f32 v[72:73], v[70:71], v[86:87]
	s_nop 0
	v_pk_add_f32 v[88:89], v[72:73], v[72:73] op_sel_hi:[0,1]
	v_fma_f32 v71, v90, s92, -v159
	v_fma_f32 v72, v74, s92, -v159
	v_exp_f32_e32 v71, v71
	v_exp_f32_e32 v87, v72
	v_fma_f32 v72, v91, s92, -v159
	v_fma_f32 v74, v75, s92, -v159
	v_exp_f32_e32 v72, v72
	v_exp_f32_e32 v88, v74
	v_add_f32_e32 v73, v71, v87
	v_pk_add_f32 v[74:75], v[72:73], v[88:89]
	s_nop 0
	v_pk_add_f32 v[90:91], v[74:75], v[74:75] op_sel_hi:[0,1]
	v_fma_f32 v74, v76, s92, -v159
	v_fma_f32 v73, v92, s92, -v159
	v_exp_f32_e32 v89, v74
	v_fma_f32 v74, v93, s92, -v159
	v_exp_f32_e32 v73, v73
	v_exp_f32_e32 v162, v74
	v_fma_f32 v74, v77, s92, -v159
	v_exp_f32_e32 v90, v74
	v_add_f32_e32 v163, v73, v89
	v_pk_add_f32 v[74:75], v[162:163], v[90:91]
	s_nop 0
	v_pk_add_f32 v[92:93], v[74:75], v[74:75] op_sel_hi:[0,1]
	v_fma_f32 v74, v94, s92, -v159
	v_exp_f32_e32 v91, v74
	v_fma_f32 v74, v78, s92, -v159
	v_exp_f32_e32 v163, v74
	v_fma_f32 v74, v95, s92, -v159
	v_exp_f32_e32 v76, v74
	v_fma_f32 v74, v79, s92, -v159
	v_exp_f32_e32 v92, v74
	v_add_f32_e32 v77, v91, v163
	v_cvt_pk_bf16_f32 v79, v161, v82
	v_cvt_pk_bf16_f32 v78, v157, v160
	v_pk_add_f32 v[74:75], v[76:77], v[92:93]
	v_cvt_pk_bf16_f32 v76, v91, v76
	v_pk_add_f32 v[94:95], v[74:75], v[74:75] op_sel_hi:[0,1]
	v_fma_f32 v74, v96, s92, -v159
	v_exp_f32_e32 v77, v74
	v_fma_f32 v74, v80, s92, -v159
	v_exp_f32_e32 v93, v74
	v_sub_f32_e32 v74, v158, v159
	v_exp_f32_e32 v96, v74
	v_fma_f32 v74, v81, s92, -v159
	v_exp_f32_e32 v94, v74
	v_add_f32_e32 v97, v77, v93
	v_cvt_pk_bf16_f32 v81, v69, v70
	v_cvt_pk_bf16_f32 v70, v175, v0
	v_add3_u32 v0, s11, v213, v168
	v_pk_add_f32 v[74:75], v[96:97], v[94:95]
	v_cvt_pk_bf16_f32 v80, v67, v84
	v_cvt_pk_bf16_f32 v67, v89, v90
	v_add_u32_e32 v90, 0x4000, v0
	v_add_f32_e32 v146, v74, v75
	v_cvt_pk_bf16_f32 v74, v71, v72
	v_cvt_pk_bf16_f32 v75, v73, v162
	v_cvt_pk_bf16_f32 v71, v183, v66
	v_cvt_pk_bf16_f32 v72, v83, v68
	v_cvt_pk_bf16_f32 v73, v85, v86
	v_cvt_pk_bf16_f32 v66, v87, v88
	ds_read2_b64 v[82:85], v90 offset0:128 offset1:130
	ds_read2_b64 v[86:89], v90 offset0:132 offset1:134
	ds_read2_b64 v[158:161], v90 offset0:136 offset1:138
	ds_read2_b64 v[218:221], v90 offset0:140 offset1:142
	s_waitcnt lgkmcnt(4)
	s_waitcnt lgkmcnt(3)
	v_mfma_f32_32x32x16_bf16 v[50:65], v[82:85], v[78:81], v[50:65]
	v_add_u32_e32 v250, 0x5000, v0
	ds_read2_b64 v[222:225], v250 offset0:160 offset1:162
	v_cvt_pk_bf16_f32 v77, v77, v96
	v_cvt_pk_bf16_f32 v68, v163, v92
	v_cvt_pk_bf16_f32 v69, v93, v94
	s_add_i32 s11, s10, 0
	s_add_u32 s2, s2, s8
	s_addc_u32 s3, s3, 0
	s_waitcnt lgkmcnt(3)
	v_mfma_f32_32x32x16_bf16 v[50:65], v[86:89], v[74:77], v[50:65]
	v_add_u32_e32 v250, 0x5000, v0
	ds_read2_b64 v[226:229], v250 offset0:164 offset1:166
	v_add_u32_e32 v86, 0x5000, v0
	v_fmac_f32_e32 v146, v156, v154
	s_cmp_eq_u32 s9, s7
	s_waitcnt lgkmcnt(3)
	v_mfma_f32_32x32x16_bf16 v[50:65], v[158:161], v[70:73], v[50:65]
	ds_read2_b64 v[158:161], v86 offset0:168 offset1:170
	s_waitcnt lgkmcnt(3)
	v_mfma_f32_32x32x16_bf16 v[50:65], v[218:221], v[66:69], v[50:65]
	ds_read2_b64 v[218:221], v86 offset0:172 offset1:174
	s_waitcnt lgkmcnt(3)
	v_mfma_f32_32x32x16_bf16 v[34:49], v[222:225], v[78:81], v[34:49]
	v_add_u32_e32 v250, 0x6000, v0
	ds_read2_b64 v[222:225], v250 offset0:192 offset1:194
	s_waitcnt lgkmcnt(3)
	v_mfma_f32_32x32x16_bf16 v[34:49], v[226:229], v[74:77], v[34:49]
	v_add_u32_e32 v250, 0x6000, v0
	ds_read2_b64 v[226:229], v250 offset0:196 offset1:198
	s_waitcnt lgkmcnt(3)
	v_mfma_f32_32x32x16_bf16 v[34:49], v[158:161], v[70:73], v[34:49]
	v_add_u32_e32 v250, 0x6000, v0
	ds_read2_b64 v[158:161], v250 offset0:200 offset1:202
	v_add_u32_e32 v86, 0x6000, v0
	v_add_u32_e32 v0, 0x7000, v0
	s_waitcnt lgkmcnt(3)
	v_mfma_f32_32x32x16_bf16 v[34:49], v[218:221], v[66:69], v[34:49]
	ds_read2_b64 v[218:221], v86 offset0:204 offset1:206
	s_waitcnt lgkmcnt(3)
	v_mfma_f32_32x32x16_bf16 v[18:33], v[222:225], v[78:81], v[18:33]
	ds_read2_b64 v[222:225], v0 offset0:224 offset1:226
	s_waitcnt lgkmcnt(3)
	v_mfma_f32_32x32x16_bf16 v[18:33], v[226:229], v[74:77], v[18:33]
	ds_read2_b64 v[226:229], v0 offset0:228 offset1:230
	s_waitcnt lgkmcnt(3)
	v_mfma_f32_32x32x16_bf16 v[18:33], v[158:161], v[70:73], v[18:33]
	ds_read2_b64 v[158:161], v0 offset0:232 offset1:234
	s_waitcnt lgkmcnt(3)
	v_mfma_f32_32x32x16_bf16 v[18:33], v[218:221], v[66:69], v[18:33]
	s_waitcnt lgkmcnt(2)
	v_mfma_f32_32x32x16_bf16 v[2:17], v[222:225], v[78:81], v[2:17]
	s_waitcnt lgkmcnt(1)
	v_mfma_f32_32x32x16_bf16 v[2:17], v[226:229], v[74:77], v[2:17]
	s_waitcnt lgkmcnt(0)
	v_mfma_f32_32x32x16_bf16 v[2:17], v[158:161], v[70:73], v[2:17]
	ds_read2_b64 v[70:73], v0 offset0:236 offset1:238
	v_add_u32_e32 v0, s11, v181
	s_waitcnt vmcnt(3)
	ds_write_b128 v0, v[142:145]
	v_add_u32_e32 v0, s11, v210
	s_waitcnt vmcnt(2)
	ds_write_b128 v0, v[138:141]
	v_add_u32_e32 v0, s10, v155
	s_waitcnt vmcnt(1)
	ds_write_b16 v0, v134 offset:17408
	ds_write_b16_d16_hi v0, v134 offset:17544
	ds_write_b16 v0, v135 offset:17680
	ds_write_b16_d16_hi v0, v135 offset:17816
	ds_write_b16 v0, v136 offset:17952
	ds_write_b16_d16_hi v0, v136 offset:18088
	ds_write_b16 v0, v137 offset:18224
	ds_write_b16_d16_hi v0, v137 offset:18360
	s_waitcnt vmcnt(0)
	ds_write_b16 v0, v130 offset:18496
	ds_write_b16_d16_hi v0, v130 offset:18632
	ds_write_b16 v0, v131 offset:18768
	ds_write_b16_d16_hi v0, v131 offset:18904
	ds_write_b16 v0, v132 offset:19040
	ds_write_b16_d16_hi v0, v132 offset:19176
	ds_write_b16 v0, v133 offset:19312
	ds_write_b16_d16_hi v0, v133 offset:19448
	s_waitcnt lgkmcnt(14)
	v_mfma_f32_32x32x16_bf16 v[2:17], v[70:73], v[66:69], v[2:17]
	s_waitcnt lgkmcnt(0)
	s_barrier
	s_cbranch_scc1 .LBB0_812
	v_mov_b32_e32 v156, v146
	s_branch .LBB0_808
